# residual epilogues (P6, P8): row sum-of-squares lane exchanges by v_permlane16/32_swap instead of ds_bpermute (32 sites)
# baseline (speedup 1.0000x reference)
.LBB0_1458:
	v_lshl_add_u32 v204, s58, 8, v212
	v_lshl_or_b32 v200, s56, 8, v214
	v_ashrrev_i32_e32 v201, 31, v200
	v_ashrrev_i32_e32 v205, 31, v204
	v_lshl_add_u64 v[202:203], v[200:201], 2, s[38:39]
	v_lshlrev_b64 v[114:115], 13, v[204:205]
	v_lshl_add_u64 v[114:115], v[202:203], 0, v[114:115]
	flat_load_dwordx4 v[216:219], v[114:115]
	flat_load_dwordx4 v[232:235], v[114:115] offset:16
	flat_load_dwordx4 v[236:239], v[114:115] offset:512
	flat_load_dwordx4 v[240:243], v[114:115] offset:528
	v_or_b32_e32 v210, 16, v204
	v_ashrrev_i32_e32 v211, 31, v210
	v_lshlrev_b64 v[114:115], 13, v[210:211]
	v_or_b32_e32 v208, 32, v204
	v_lshl_add_u64 v[114:115], v[202:203], 0, v[114:115]
	v_ashrrev_i32_e32 v209, 31, v208
	flat_load_dwordx4 v[174:177], v[114:115]
	flat_load_dwordx4 v[170:173], v[114:115] offset:16
	flat_load_dwordx4 v[166:169], v[114:115] offset:512
	flat_load_dwordx4 v[162:165], v[114:115] offset:528
	v_lshlrev_b64 v[114:115], 13, v[208:209]
	v_or_b32_e32 v206, 48, v204
	v_lshl_add_u64 v[114:115], v[202:203], 0, v[114:115]
	v_ashrrev_i32_e32 v207, 31, v206
	flat_load_dwordx4 v[158:161], v[114:115]
	flat_load_dwordx4 v[154:157], v[114:115] offset:16
	flat_load_dwordx4 v[134:137], v[114:115] offset:512
	flat_load_dwordx4 v[130:133], v[114:115] offset:528
	v_lshlrev_b64 v[114:115], 13, v[206:207]
	v_lshl_add_u64 v[114:115], v[202:203], 0, v[114:115]
	flat_load_dwordx4 v[142:145], v[114:115]
	flat_load_dwordx4 v[138:141], v[114:115] offset:16
	flat_load_dwordx4 v[118:121], v[114:115] offset:512
	s_nop 0
	flat_load_dwordx4 v[114:117], v[114:115] offset:528
	v_lshlrev_b64 v[220:221], 11, v[204:205]
	v_lshl_add_u64 v[220:221], v[220:221], 0, v[200:201]
	s_waitcnt vmcnt(0) lgkmcnt(0)
	v_pk_add_f32 v[152:153], v[152:153], v[218:219]
	v_pk_add_f32 v[150:151], v[150:151], v[216:217]
	v_pk_add_f32 v[146:147], v[146:147], v[232:233]
	v_lshl_add_u64 v[232:233], v[220:221], 2, s[0:1]
	v_pk_add_f32 v[148:149], v[148:149], v[234:235]
	flat_store_dwordx4 v[232:233], v[150:153]
	flat_store_dwordx4 v[232:233], v[146:149] offset:16
	v_cvt_pk_bf16_f32 v216, v150, v151
	v_cvt_pk_bf16_f32 v217, v152, v153
	v_cvt_pk_bf16_f32 v218, v146, v147
	v_lshlrev_b64 v[220:221], 1, v[220:221]
	v_mul_f32_e32 v151, v151, v151
	v_fmac_f32_e32 v151, v150, v150
	v_mul_f32_e32 v150, v153, v153
	v_fmac_f32_e32 v150, v152, v152
	v_mul_f32_e32 v147, v147, v147
	v_add_f32_e32 v150, v151, v150
	v_fmac_f32_e32 v147, v146, v146
	v_add_f32_e32 v146, v150, v147
	v_mul_f32_e32 v147, v149, v149
	v_lshl_add_u64 v[234:235], s[6:7], 0, v[220:221]
	v_fmac_f32_e32 v147, v148, v148
	v_pk_add_f32 v[128:129], v[128:129], v[238:239]
	v_pk_add_f32 v[126:127], v[126:127], v[236:237]
	v_cvt_pk_bf16_f32 v219, v148, v149
	flat_store_dwordx4 v[234:235], v[216:219]
	v_add_f32_e32 v152, v147, v146
	v_pk_add_f32 v[124:125], v[124:125], v[242:243]
	v_pk_add_f32 v[122:123], v[122:123], v[240:241]
	flat_store_dwordx4 v[232:233], v[126:129] offset:512
	flat_store_dwordx4 v[232:233], v[122:125] offset:528
	v_cvt_pk_bf16_f32 v146, v126, v127
	v_cvt_pk_bf16_f32 v147, v128, v129
	v_cvt_pk_bf16_f32 v148, v122, v123
	v_cvt_pk_bf16_f32 v149, v124, v125
	s_nop 0
	v_mul_f32_e32 v127, v127, v127
	v_fmac_f32_e32 v127, v126, v126
	v_mul_f32_e32 v126, v129, v129
	v_fmac_f32_e32 v126, v128, v128
	v_mul_f32_e32 v123, v123, v123
	v_add_f32_e32 v126, v127, v126
	v_fmac_f32_e32 v123, v122, v122
	v_add_f32_e32 v122, v126, v123
	v_mul_f32_e32 v123, v125, v125
	v_fmac_f32_e32 v123, v124, v124
	v_and_b32_e32 v124, 64, v226
	v_add_f32_e32 v122, v123, v122
	v_xor_b32_e32 v123, 16, v226
	v_add_u32_e32 v125, 64, v124
	v_or_b32_e32 v220, 0x100, v220
	v_cmp_lt_i32_e32 vcc, v123, v125
	v_lshl_add_u64 v[150:151], s[6:7], 0, v[220:221]
	flat_store_dwordx4 v[150:151], v[146:149]
	v_cndmask_b32_e32 v123, v226, v123, vcc
	v_add_f32_e32 v122, v152, v122
	v_lshlrev_b32_e32 v146, 2, v123
	v_mov_b32_e32 v123, v122
	s_nop 1
	v_permlane16_swap_b32 v123, v123
	s_waitcnt lgkmcnt(0)
	v_add_f32_e32 v124, v122, v123
	v_xor_b32_e32 v122, 32, v226
	v_cmp_lt_i32_e32 vcc, v122, v125
	s_nop 1
	v_cndmask_b32_e32 v122, v226, v122, vcc
	v_lshlrev_b32_e32 v147, 2, v122
	v_mov_b32_e32 v125, v124
	s_nop 1
	v_permlane32_swap_b32 v125, v125
	v_lshl_add_u64 v[122:123], v[204:205], 2, s[44:45]
	s_and_saveexec_b64 s[56:57], s[40:41]
	s_cbranch_execz .LBB0_1460
	s_waitcnt lgkmcnt(0)
	v_add_f32_e32 v124, v124, v125
	flat_atomic_add_f32 v[122:123], v124
.LBB0_1460:
	s_or_b64 exec, exec, s[56:57]
	s_waitcnt lgkmcnt(0)
	v_lshlrev_b64 v[124:125], 11, v[210:211]
	v_lshl_add_u64 v[128:129], v[124:125], 0, v[200:201]
	v_pk_add_f32 v[112:113], v[112:113], v[176:177]
	v_pk_add_f32 v[110:111], v[110:111], v[174:175]
	v_lshl_add_u64 v[148:149], v[128:129], 2, s[0:1]
	v_pk_add_f32 v[108:109], v[108:109], v[172:173]
	v_pk_add_f32 v[106:107], v[106:107], v[170:171]
	flat_store_dwordx4 v[148:149], v[110:113]
	flat_store_dwordx4 v[148:149], v[106:109] offset:16
	v_cvt_pk_bf16_f32 v124, v110, v111
	v_cvt_pk_bf16_f32 v125, v112, v113
	v_cvt_pk_bf16_f32 v126, v106, v107
	v_pk_add_f32 v[104:105], v[104:105], v[168:169]
	v_mul_f32_e32 v111, v111, v111
	v_fmac_f32_e32 v111, v110, v110
	v_mul_f32_e32 v110, v113, v113
	v_fmac_f32_e32 v110, v112, v112
	v_mul_f32_e32 v107, v107, v107
	v_add_f32_e32 v110, v111, v110
	v_fmac_f32_e32 v107, v106, v106
	v_add_f32_e32 v106, v110, v107
	v_mul_f32_e32 v107, v109, v109
	v_fmac_f32_e32 v107, v108, v108
	v_pk_add_f32 v[102:103], v[102:103], v[166:167]
	v_cvt_pk_bf16_f32 v127, v108, v109
	v_add_f32_e32 v106, v107, v106
	v_mul_f32_e32 v107, v103, v103
	v_mul_f32_e32 v108, v105, v105
	v_pk_add_f32 v[98:99], v[98:99], v[162:163]
	v_fmac_f32_e32 v107, v102, v102
	v_fmac_f32_e32 v108, v104, v104
	v_add_f32_e32 v107, v107, v108
	v_mul_f32_e32 v108, v99, v99
	v_pk_add_f32 v[100:101], v[100:101], v[164:165]
	v_fmac_f32_e32 v108, v98, v98
	v_add_f32_e32 v107, v107, v108
	v_mul_f32_e32 v108, v101, v101
	v_fmac_f32_e32 v108, v100, v100
	v_add_f32_e32 v107, v108, v107
	v_add_f32_e32 v106, v106, v107
	v_mov_b32_e32 v107, v106
	s_nop 1
	v_permlane16_swap_b32 v107, v107
	v_lshlrev_b64 v[128:129], 1, v[128:129]
	v_lshl_add_u64 v[150:151], s[6:7], 0, v[128:129]
	flat_store_dwordx4 v[150:151], v[124:127]
	flat_store_dwordx4 v[148:149], v[102:105] offset:512
	flat_store_dwordx4 v[148:149], v[98:101] offset:528
	v_or_b32_e32 v128, 0x100, v128
	v_cvt_pk_bf16_f32 v102, v102, v103
	v_cvt_pk_bf16_f32 v103, v104, v105
	v_cvt_pk_bf16_f32 v104, v98, v99
	v_cvt_pk_bf16_f32 v105, v100, v101
	s_waitcnt lgkmcnt(0)
	v_add_f32_e32 v98, v106, v107
	v_mov_b32_e32 v99, v98
	s_nop 1
	v_permlane32_swap_b32 v99, v99
	v_lshl_add_u64 v[100:101], s[6:7], 0, v[128:129]
	flat_store_dwordx4 v[100:101], v[102:105]
	s_and_saveexec_b64 s[56:57], s[40:41]
	s_cbranch_execz .LBB0_1462
	s_waitcnt lgkmcnt(0)
	v_add_f32_e32 v98, v98, v99
	flat_atomic_add_f32 v[122:123], v98 offset:64
.LBB0_1462:
	s_or_b64 exec, exec, s[56:57]
	s_waitcnt lgkmcnt(0)
	v_lshlrev_b64 v[98:99], 11, v[208:209]
	v_lshl_add_u64 v[102:103], v[98:99], 0, v[200:201]
	v_pk_add_f32 v[96:97], v[96:97], v[160:161]
	v_pk_add_f32 v[94:95], v[94:95], v[158:159]
	v_lshl_add_u64 v[104:105], v[102:103], 2, s[0:1]
	v_pk_add_f32 v[92:93], v[92:93], v[156:157]
	v_pk_add_f32 v[90:91], v[90:91], v[154:155]
	flat_store_dwordx4 v[104:105], v[94:97]
	flat_store_dwordx4 v[104:105], v[90:93] offset:16
	v_cvt_pk_bf16_f32 v98, v94, v95
	v_cvt_pk_bf16_f32 v99, v96, v97
	v_cvt_pk_bf16_f32 v100, v90, v91
	v_pk_add_f32 v[88:89], v[88:89], v[136:137]
	v_mul_f32_e32 v95, v95, v95
	v_fmac_f32_e32 v95, v94, v94
	v_mul_f32_e32 v94, v97, v97
	v_fmac_f32_e32 v94, v96, v96
	v_mul_f32_e32 v91, v91, v91
	v_add_f32_e32 v94, v95, v94
	v_fmac_f32_e32 v91, v90, v90
	v_add_f32_e32 v90, v94, v91
	v_mul_f32_e32 v91, v93, v93
	v_fmac_f32_e32 v91, v92, v92
	v_pk_add_f32 v[86:87], v[86:87], v[134:135]
	v_cvt_pk_bf16_f32 v101, v92, v93
	v_add_f32_e32 v90, v91, v90
	v_mul_f32_e32 v91, v87, v87
	v_mul_f32_e32 v92, v89, v89
	v_pk_add_f32 v[82:83], v[82:83], v[130:131]
	v_fmac_f32_e32 v91, v86, v86
	v_fmac_f32_e32 v92, v88, v88
	v_add_f32_e32 v91, v91, v92
	v_mul_f32_e32 v92, v83, v83
	v_pk_add_f32 v[84:85], v[84:85], v[132:133]
	v_fmac_f32_e32 v92, v82, v82
	v_add_f32_e32 v91, v91, v92
	v_mul_f32_e32 v92, v85, v85
	v_fmac_f32_e32 v92, v84, v84
	v_add_f32_e32 v91, v92, v91
	v_add_f32_e32 v90, v90, v91
	v_mov_b32_e32 v91, v90
	s_nop 1
	v_permlane16_swap_b32 v91, v91
	v_lshlrev_b64 v[102:103], 1, v[102:103]
	v_lshl_add_u64 v[106:107], s[6:7], 0, v[102:103]
	flat_store_dwordx4 v[106:107], v[98:101]
	flat_store_dwordx4 v[104:105], v[86:89] offset:512
	flat_store_dwordx4 v[104:105], v[82:85] offset:528
	v_or_b32_e32 v102, 0x100, v102
	v_cvt_pk_bf16_f32 v86, v86, v87
	v_cvt_pk_bf16_f32 v87, v88, v89
	v_cvt_pk_bf16_f32 v88, v82, v83
	v_cvt_pk_bf16_f32 v89, v84, v85
	s_waitcnt lgkmcnt(0)
	v_add_f32_e32 v82, v90, v91
	v_mov_b32_e32 v83, v82
	s_nop 1
	v_permlane32_swap_b32 v83, v83
	v_lshl_add_u64 v[84:85], s[6:7], 0, v[102:103]
	flat_store_dwordx4 v[84:85], v[86:89]
	s_and_saveexec_b64 s[56:57], s[40:41]
	s_cbranch_execz .LBB0_1464
	s_waitcnt lgkmcnt(0)
	v_add_f32_e32 v82, v82, v83
	flat_atomic_add_f32 v[122:123], v82 offset:128
.LBB0_1464:
	s_or_b64 exec, exec, s[56:57]
	s_waitcnt lgkmcnt(0)
	v_lshlrev_b64 v[82:83], 11, v[206:207]
	v_lshl_add_u64 v[86:87], v[82:83], 0, v[200:201]
	v_pk_add_f32 v[80:81], v[80:81], v[144:145]
	v_pk_add_f32 v[78:79], v[78:79], v[142:143]
	v_lshl_add_u64 v[88:89], v[86:87], 2, s[0:1]
	v_pk_add_f32 v[76:77], v[76:77], v[140:141]
	v_pk_add_f32 v[74:75], v[74:75], v[138:139]
	flat_store_dwordx4 v[88:89], v[78:81]
	flat_store_dwordx4 v[88:89], v[74:77] offset:16
	v_cvt_pk_bf16_f32 v82, v78, v79
	v_cvt_pk_bf16_f32 v83, v80, v81
	v_cvt_pk_bf16_f32 v84, v74, v75
	v_pk_add_f32 v[72:73], v[72:73], v[120:121]
	v_mul_f32_e32 v79, v79, v79
	v_fmac_f32_e32 v79, v78, v78
	v_mul_f32_e32 v78, v81, v81
	v_fmac_f32_e32 v78, v80, v80
	v_mul_f32_e32 v75, v75, v75
	v_add_f32_e32 v78, v79, v78
	v_fmac_f32_e32 v75, v74, v74
	v_add_f32_e32 v74, v78, v75
	v_mul_f32_e32 v75, v77, v77
	v_fmac_f32_e32 v75, v76, v76
	v_pk_add_f32 v[70:71], v[70:71], v[118:119]
	v_cvt_pk_bf16_f32 v85, v76, v77
	v_add_f32_e32 v74, v75, v74
	v_mul_f32_e32 v75, v71, v71
	v_mul_f32_e32 v76, v73, v73
	v_pk_add_f32 v[66:67], v[66:67], v[114:115]
	v_fmac_f32_e32 v75, v70, v70
	v_fmac_f32_e32 v76, v72, v72
	v_add_f32_e32 v75, v75, v76
	v_mul_f32_e32 v76, v67, v67
	v_pk_add_f32 v[68:69], v[68:69], v[116:117]
	v_fmac_f32_e32 v76, v66, v66
	v_add_f32_e32 v75, v75, v76
	v_mul_f32_e32 v76, v69, v69
	v_fmac_f32_e32 v76, v68, v68
	v_add_f32_e32 v75, v76, v75
	v_add_f32_e32 v74, v74, v75
	v_mov_b32_e32 v75, v74
	s_nop 1
	v_permlane16_swap_b32 v75, v75
	v_lshlrev_b64 v[86:87], 1, v[86:87]
	v_lshl_add_u64 v[90:91], s[6:7], 0, v[86:87]
	flat_store_dwordx4 v[90:91], v[82:85]
	flat_store_dwordx4 v[88:89], v[70:73] offset:512
	flat_store_dwordx4 v[88:89], v[66:69] offset:528
	v_or_b32_e32 v86, 0x100, v86
	v_cvt_pk_bf16_f32 v70, v70, v71
	v_cvt_pk_bf16_f32 v71, v72, v73
	v_cvt_pk_bf16_f32 v72, v66, v67
	v_cvt_pk_bf16_f32 v73, v68, v69
	s_waitcnt lgkmcnt(0)
	v_add_f32_e32 v66, v74, v75
	v_mov_b32_e32 v67, v66
	s_nop 1
	v_permlane32_swap_b32 v67, v67
	v_lshl_add_u64 v[68:69], s[6:7], 0, v[86:87]
	flat_store_dwordx4 v[68:69], v[70:73]
	s_and_saveexec_b64 s[56:57], s[40:41]
	s_cbranch_execz .LBB0_1466
	s_waitcnt lgkmcnt(0)
	v_add_f32_e32 v66, v66, v67
	flat_atomic_add_f32 v[122:123], v66 offset:192
.LBB0_1466:
	s_or_b64 exec, exec, s[56:57]
	v_add_u32_e32 v138, 0x80, v204
	v_ashrrev_i32_e32 v139, 31, v138
	s_waitcnt lgkmcnt(0)
	v_lshlrev_b64 v[66:67], 13, v[138:139]
	v_lshl_add_u64 v[66:67], v[202:203], 0, v[66:67]
	flat_load_dwordx4 v[130:133], v[66:67]
	flat_load_dwordx4 v[134:137], v[66:67] offset:16
	flat_load_dwordx4 v[118:121], v[66:67] offset:512
	flat_load_dwordx4 v[114:117], v[66:67] offset:528
	v_add_u32_e32 v128, 0x90, v204
	v_ashrrev_i32_e32 v129, 31, v128
	v_lshlrev_b64 v[66:67], 13, v[128:129]
	v_add_u32_e32 v126, 0xa0, v204
	v_lshl_add_u64 v[66:67], v[202:203], 0, v[66:67]
	v_ashrrev_i32_e32 v127, 31, v126
	flat_load_dwordx4 v[110:113], v[66:67]
	flat_load_dwordx4 v[106:109], v[66:67] offset:16
	flat_load_dwordx4 v[102:105], v[66:67] offset:512
	flat_load_dwordx4 v[98:101], v[66:67] offset:528
	v_lshlrev_b64 v[66:67], 13, v[126:127]
	v_add_u32_e32 v124, 0xb0, v204
	v_lshl_add_u64 v[66:67], v[202:203], 0, v[66:67]
	v_ashrrev_i32_e32 v125, 31, v124
	flat_load_dwordx4 v[94:97], v[66:67]
	flat_load_dwordx4 v[90:93], v[66:67] offset:16
	flat_load_dwordx4 v[78:81], v[66:67] offset:512
	flat_load_dwordx4 v[74:77], v[66:67] offset:528
	v_lshlrev_b64 v[66:67], 13, v[124:125]
	v_lshl_add_u64 v[66:67], v[202:203], 0, v[66:67]
	flat_load_dwordx4 v[86:89], v[66:67]
	flat_load_dwordx4 v[82:85], v[66:67] offset:16
	flat_load_dwordx4 v[70:73], v[66:67] offset:512
	s_nop 0
	flat_load_dwordx4 v[66:69], v[66:67] offset:528
	v_lshlrev_b64 v[138:139], 11, v[138:139]
	v_lshl_add_u64 v[138:139], v[138:139], 0, v[200:201]
	s_waitcnt vmcnt(0) lgkmcnt(0)
	v_pk_add_f32 v[64:65], v[64:65], v[132:133]
	v_pk_add_f32 v[62:63], v[62:63], v[130:131]
	v_pk_add_f32 v[58:59], v[58:59], v[134:135]
	v_lshl_add_u64 v[134:135], v[138:139], 2, s[0:1]
	v_pk_add_f32 v[60:61], v[60:61], v[136:137]
	flat_store_dwordx4 v[134:135], v[62:65]
	flat_store_dwordx4 v[134:135], v[58:61] offset:16
	v_cvt_pk_bf16_f32 v130, v62, v63
	v_cvt_pk_bf16_f32 v131, v64, v65
	v_cvt_pk_bf16_f32 v132, v58, v59
	v_lshlrev_b64 v[136:137], 1, v[138:139]
	v_mul_f32_e32 v63, v63, v63
	v_fmac_f32_e32 v63, v62, v62
	v_mul_f32_e32 v62, v65, v65
	v_fmac_f32_e32 v62, v64, v64
	v_mul_f32_e32 v59, v59, v59
	v_add_f32_e32 v62, v63, v62
	v_fmac_f32_e32 v59, v58, v58
	v_add_f32_e32 v58, v62, v59
	v_mul_f32_e32 v59, v61, v61
	v_lshl_add_u64 v[138:139], s[6:7], 0, v[136:137]
	v_fmac_f32_e32 v59, v60, v60
	v_pk_add_f32 v[56:57], v[56:57], v[120:121]
	v_pk_add_f32 v[54:55], v[54:55], v[118:119]
	v_cvt_pk_bf16_f32 v133, v60, v61
	flat_store_dwordx4 v[138:139], v[130:133]
	v_add_f32_e32 v64, v59, v58
	v_pk_add_f32 v[52:53], v[52:53], v[116:117]
	v_pk_add_f32 v[50:51], v[50:51], v[114:115]
	flat_store_dwordx4 v[134:135], v[54:57] offset:512
	flat_store_dwordx4 v[134:135], v[50:53] offset:528
	v_cvt_pk_bf16_f32 v58, v54, v55
	v_cvt_pk_bf16_f32 v59, v56, v57
	v_cvt_pk_bf16_f32 v60, v50, v51
	v_or_b32_e32 v136, 0x100, v136
	v_mul_f32_e32 v55, v55, v55
	v_fmac_f32_e32 v55, v54, v54
	v_mul_f32_e32 v54, v57, v57
	v_fmac_f32_e32 v54, v56, v56
	v_mul_f32_e32 v51, v51, v51
	v_add_f32_e32 v54, v55, v54
	v_fmac_f32_e32 v51, v50, v50
	v_add_f32_e32 v50, v54, v51
	v_mul_f32_e32 v51, v53, v53
	v_fmac_f32_e32 v51, v52, v52
	v_add_f32_e32 v50, v51, v50
	v_add_f32_e32 v50, v64, v50
	v_mov_b32_e32 v51, v50
	s_nop 1
	v_permlane16_swap_b32 v51, v51
	v_lshl_add_u64 v[62:63], s[6:7], 0, v[136:137]
	v_cvt_pk_bf16_f32 v61, v52, v53
	flat_store_dwordx4 v[62:63], v[58:61]
	s_waitcnt lgkmcnt(0)
	v_add_f32_e32 v50, v50, v51
	v_mov_b32_e32 v51, v50
	s_nop 1
	v_permlane32_swap_b32 v51, v51
	s_and_saveexec_b64 s[56:57], s[40:41]
	s_cbranch_execz .LBB0_1468
	s_waitcnt lgkmcnt(0)
	v_add_f32_e32 v50, v50, v51
	flat_atomic_add_f32 v[122:123], v50 offset:512
.LBB0_1468:
	s_or_b64 exec, exec, s[56:57]
	s_waitcnt lgkmcnt(0)
	v_lshlrev_b64 v[50:51], 11, v[128:129]
	v_lshl_add_u64 v[54:55], v[50:51], 0, v[200:201]
	v_pk_add_f32 v[48:49], v[48:49], v[112:113]
	v_pk_add_f32 v[46:47], v[46:47], v[110:111]
	v_lshl_add_u64 v[56:57], v[54:55], 2, s[0:1]
	v_pk_add_f32 v[44:45], v[44:45], v[108:109]
	v_pk_add_f32 v[42:43], v[42:43], v[106:107]
	flat_store_dwordx4 v[56:57], v[46:49]
	flat_store_dwordx4 v[56:57], v[42:45] offset:16
	v_cvt_pk_bf16_f32 v50, v46, v47
	v_cvt_pk_bf16_f32 v51, v48, v49
	v_cvt_pk_bf16_f32 v52, v42, v43
	v_pk_add_f32 v[40:41], v[40:41], v[104:105]
	v_mul_f32_e32 v47, v47, v47
	v_fmac_f32_e32 v47, v46, v46
	v_mul_f32_e32 v46, v49, v49
	v_fmac_f32_e32 v46, v48, v48
	v_mul_f32_e32 v43, v43, v43
	v_add_f32_e32 v46, v47, v46
	v_fmac_f32_e32 v43, v42, v42
	v_add_f32_e32 v42, v46, v43
	v_mul_f32_e32 v43, v45, v45
	v_fmac_f32_e32 v43, v44, v44
	v_pk_add_f32 v[38:39], v[38:39], v[102:103]
	v_cvt_pk_bf16_f32 v53, v44, v45
	v_add_f32_e32 v42, v43, v42
	v_mul_f32_e32 v43, v39, v39
	v_mul_f32_e32 v44, v41, v41
	v_pk_add_f32 v[34:35], v[34:35], v[98:99]
	v_fmac_f32_e32 v43, v38, v38
	v_fmac_f32_e32 v44, v40, v40
	v_add_f32_e32 v43, v43, v44
	v_mul_f32_e32 v44, v35, v35
	v_pk_add_f32 v[36:37], v[36:37], v[100:101]
	v_fmac_f32_e32 v44, v34, v34
	v_add_f32_e32 v43, v43, v44
	v_mul_f32_e32 v44, v37, v37
	v_fmac_f32_e32 v44, v36, v36
	v_add_f32_e32 v43, v44, v43
	v_add_f32_e32 v42, v42, v43
	v_mov_b32_e32 v43, v42
	s_nop 1
	v_permlane16_swap_b32 v43, v43
	v_lshlrev_b64 v[54:55], 1, v[54:55]
	v_lshl_add_u64 v[58:59], s[6:7], 0, v[54:55]
	flat_store_dwordx4 v[58:59], v[50:53]
	flat_store_dwordx4 v[56:57], v[38:41] offset:512
	flat_store_dwordx4 v[56:57], v[34:37] offset:528
	v_or_b32_e32 v54, 0x100, v54
	v_cvt_pk_bf16_f32 v38, v38, v39
	v_cvt_pk_bf16_f32 v39, v40, v41
	v_cvt_pk_bf16_f32 v40, v34, v35
	v_cvt_pk_bf16_f32 v41, v36, v37
	s_waitcnt lgkmcnt(0)
	v_add_f32_e32 v34, v42, v43
	v_mov_b32_e32 v35, v34
	s_nop 1
	v_permlane32_swap_b32 v35, v35
	v_lshl_add_u64 v[36:37], s[6:7], 0, v[54:55]
	flat_store_dwordx4 v[36:37], v[38:41]
	s_and_saveexec_b64 s[56:57], s[40:41]
	s_cbranch_execz .LBB0_1470
	s_waitcnt lgkmcnt(0)
	v_add_f32_e32 v34, v34, v35
	flat_atomic_add_f32 v[122:123], v34 offset:576
.LBB0_1470:
	s_or_b64 exec, exec, s[56:57]
	s_waitcnt lgkmcnt(0)
	v_lshlrev_b64 v[34:35], 11, v[126:127]
	v_lshl_add_u64 v[38:39], v[34:35], 0, v[200:201]
	v_pk_add_f32 v[32:33], v[32:33], v[96:97]
	v_pk_add_f32 v[30:31], v[30:31], v[94:95]
	v_lshl_add_u64 v[40:41], v[38:39], 2, s[0:1]
	v_pk_add_f32 v[28:29], v[28:29], v[92:93]
	v_pk_add_f32 v[26:27], v[26:27], v[90:91]
	flat_store_dwordx4 v[40:41], v[30:33]
	flat_store_dwordx4 v[40:41], v[26:29] offset:16
	v_cvt_pk_bf16_f32 v34, v30, v31
	v_cvt_pk_bf16_f32 v35, v32, v33
	v_cvt_pk_bf16_f32 v36, v26, v27
	v_pk_add_f32 v[24:25], v[24:25], v[80:81]
	v_mul_f32_e32 v31, v31, v31
	v_fmac_f32_e32 v31, v30, v30
	v_mul_f32_e32 v30, v33, v33
	v_fmac_f32_e32 v30, v32, v32
	v_mul_f32_e32 v27, v27, v27
	v_add_f32_e32 v30, v31, v30
	v_fmac_f32_e32 v27, v26, v26
	v_add_f32_e32 v26, v30, v27
	v_mul_f32_e32 v27, v29, v29
	v_fmac_f32_e32 v27, v28, v28
	v_pk_add_f32 v[22:23], v[22:23], v[78:79]
	v_cvt_pk_bf16_f32 v37, v28, v29
	v_add_f32_e32 v26, v27, v26
	v_mul_f32_e32 v27, v23, v23
	v_mul_f32_e32 v28, v25, v25
	v_pk_add_f32 v[18:19], v[18:19], v[74:75]
	v_fmac_f32_e32 v27, v22, v22
	v_fmac_f32_e32 v28, v24, v24
	v_add_f32_e32 v27, v27, v28
	v_mul_f32_e32 v28, v19, v19
	v_pk_add_f32 v[20:21], v[20:21], v[76:77]
	v_fmac_f32_e32 v28, v18, v18
	v_add_f32_e32 v27, v27, v28
	v_mul_f32_e32 v28, v21, v21
	v_fmac_f32_e32 v28, v20, v20
	v_add_f32_e32 v27, v28, v27
	v_add_f32_e32 v26, v26, v27
	v_mov_b32_e32 v27, v26
	s_nop 1
	v_permlane16_swap_b32 v27, v27
	v_lshlrev_b64 v[38:39], 1, v[38:39]
	v_lshl_add_u64 v[42:43], s[6:7], 0, v[38:39]
	flat_store_dwordx4 v[42:43], v[34:37]
	flat_store_dwordx4 v[40:41], v[22:25] offset:512
	flat_store_dwordx4 v[40:41], v[18:21] offset:528
	v_or_b32_e32 v38, 0x100, v38
	v_cvt_pk_bf16_f32 v22, v22, v23
	v_cvt_pk_bf16_f32 v23, v24, v25
	v_cvt_pk_bf16_f32 v24, v18, v19
	v_cvt_pk_bf16_f32 v25, v20, v21
	s_waitcnt lgkmcnt(0)
	v_add_f32_e32 v18, v26, v27
	v_mov_b32_e32 v19, v18
	s_nop 1
	v_permlane32_swap_b32 v19, v19
	v_lshl_add_u64 v[20:21], s[6:7], 0, v[38:39]
	flat_store_dwordx4 v[20:21], v[22:25]
	s_and_saveexec_b64 s[56:57], s[40:41]
	s_cbranch_execz .LBB0_1472
	s_waitcnt lgkmcnt(0)
	v_add_f32_e32 v18, v18, v19
	flat_atomic_add_f32 v[122:123], v18 offset:640
.LBB0_1472:
	s_or_b64 exec, exec, s[56:57]
	s_waitcnt lgkmcnt(0)
	v_lshlrev_b64 v[18:19], 11, v[124:125]
	v_lshl_add_u64 v[22:23], v[18:19], 0, v[200:201]
	v_pk_add_f32 v[16:17], v[16:17], v[88:89]
	v_pk_add_f32 v[14:15], v[14:15], v[86:87]
	v_lshl_add_u64 v[24:25], v[22:23], 2, s[0:1]
	v_pk_add_f32 v[12:13], v[12:13], v[84:85]
	v_pk_add_f32 v[10:11], v[10:11], v[82:83]
	flat_store_dwordx4 v[24:25], v[14:17]
	flat_store_dwordx4 v[24:25], v[10:13] offset:16
	v_cvt_pk_bf16_f32 v18, v14, v15
	v_cvt_pk_bf16_f32 v19, v16, v17
	v_cvt_pk_bf16_f32 v20, v10, v11
	v_pk_add_f32 v[8:9], v[8:9], v[72:73]
	v_mul_f32_e32 v15, v15, v15
	v_fmac_f32_e32 v15, v14, v14
	v_mul_f32_e32 v14, v17, v17
	v_fmac_f32_e32 v14, v16, v16
	v_mul_f32_e32 v11, v11, v11
	v_add_f32_e32 v14, v15, v14
	v_fmac_f32_e32 v11, v10, v10
	v_add_f32_e32 v10, v14, v11
	v_mul_f32_e32 v11, v13, v13
	v_fmac_f32_e32 v11, v12, v12
	v_pk_add_f32 v[6:7], v[6:7], v[70:71]
	v_cvt_pk_bf16_f32 v21, v12, v13
	v_add_f32_e32 v10, v11, v10
	v_mul_f32_e32 v11, v7, v7
	v_mul_f32_e32 v12, v9, v9
	v_pk_add_f32 v[2:3], v[2:3], v[66:67]
	v_fmac_f32_e32 v11, v6, v6
	v_fmac_f32_e32 v12, v8, v8
	v_add_f32_e32 v11, v11, v12
	v_mul_f32_e32 v12, v3, v3
	v_pk_add_f32 v[4:5], v[4:5], v[68:69]
	v_fmac_f32_e32 v12, v2, v2
	v_add_f32_e32 v11, v11, v12
	v_mul_f32_e32 v12, v5, v5
	v_fmac_f32_e32 v12, v4, v4
	v_add_f32_e32 v11, v12, v11
	v_add_f32_e32 v10, v10, v11
	v_mov_b32_e32 v11, v10
	s_nop 1
	v_permlane16_swap_b32 v11, v11
	v_lshlrev_b64 v[22:23], 1, v[22:23]
	v_lshl_add_u64 v[26:27], s[6:7], 0, v[22:23]
	flat_store_dwordx4 v[26:27], v[18:21]
	flat_store_dwordx4 v[24:25], v[6:9] offset:512
	flat_store_dwordx4 v[24:25], v[2:5] offset:528
	v_or_b32_e32 v22, 0x100, v22
	v_cvt_pk_bf16_f32 v6, v6, v7
	v_cvt_pk_bf16_f32 v7, v8, v9
	v_cvt_pk_bf16_f32 v8, v2, v3
	v_cvt_pk_bf16_f32 v9, v4, v5
	s_waitcnt lgkmcnt(0)
	v_add_f32_e32 v2, v10, v11
	v_mov_b32_e32 v3, v2
	s_nop 1
	v_permlane32_swap_b32 v3, v3
	v_lshl_add_u64 v[4:5], s[6:7], 0, v[22:23]
	flat_store_dwordx4 v[4:5], v[6:9]
	s_and_saveexec_b64 s[56:57], s[40:41]
	s_cbranch_execz .LBB0_1474
	s_waitcnt lgkmcnt(0)
	v_add_f32_e32 v2, v2, v3
	flat_atomic_add_f32 v[122:123], v2 offset:704

.LBB0_1852:
	v_lshl_add_u32 v204, s67, 8, v218
	v_lshl_or_b32 v200, s66, 8, v220
	v_ashrrev_i32_e32 v201, 31, v200
	v_ashrrev_i32_e32 v205, 31, v204
	v_lshl_add_u64 v[202:203], v[200:201], 2, s[0:1]
	v_lshlrev_b64 v[114:115], 13, v[204:205]
	v_lshl_add_u64 v[248:249], v[202:203], 0, v[114:115]
	flat_load_dwordx4 v[232:235], v[248:249]
	flat_load_dwordx4 v[236:239], v[248:249] offset:16
	flat_load_dwordx4 v[240:243], v[248:249] offset:512
	flat_load_dwordx4 v[244:247], v[248:249] offset:528
	v_or_b32_e32 v214, 16, v204
	v_ashrrev_i32_e32 v215, 31, v214
	v_or_b32_e32 v210, 32, v204
	v_lshlrev_b64 v[114:115], 13, v[214:215]
	v_ashrrev_i32_e32 v211, 31, v210
	v_or_b32_e32 v206, 48, v204
	v_lshl_add_u64 v[216:217], v[202:203], 0, v[114:115]
	v_lshlrev_b64 v[114:115], 13, v[210:211]
	v_ashrrev_i32_e32 v207, 31, v206
	v_lshl_add_u64 v[212:213], v[202:203], 0, v[114:115]
	v_lshlrev_b64 v[114:115], 13, v[206:207]
	v_lshl_add_u64 v[208:209], v[202:203], 0, v[114:115]
	flat_load_dwordx4 v[174:177], v[216:217]
	flat_load_dwordx4 v[170:173], v[216:217] offset:16
	flat_load_dwordx4 v[166:169], v[216:217] offset:512
	flat_load_dwordx4 v[162:165], v[216:217] offset:528
	flat_load_dwordx4 v[158:161], v[212:213]
	flat_load_dwordx4 v[154:157], v[212:213] offset:16
	flat_load_dwordx4 v[134:137], v[212:213] offset:512
	flat_load_dwordx4 v[130:133], v[212:213] offset:528
	flat_load_dwordx4 v[142:145], v[208:209]
	flat_load_dwordx4 v[138:141], v[208:209] offset:16
	flat_load_dwordx4 v[118:121], v[208:209] offset:512
	flat_load_dwordx4 v[114:117], v[208:209] offset:528
	v_lshlrev_b64 v[250:251], 11, v[204:205]
	v_lshl_add_u64 v[250:251], v[250:251], 0, v[200:201]
	s_waitcnt vmcnt(0) lgkmcnt(0)
	v_readlane_b32 s100, v255, 10
	v_readlane_b32 s101, v255, 11
	v_pk_add_f32 v[152:153], v[152:153], v[234:235]
	v_pk_add_f32 v[150:151], v[150:151], v[232:233]
	v_pk_add_f32 v[148:149], v[148:149], v[238:239]
	v_pk_add_f32 v[146:147], v[146:147], v[236:237]
	flat_store_dwordx4 v[248:249], v[150:153]
	flat_store_dwordx4 v[248:249], v[146:149] offset:16
	v_cvt_pk_bf16_f32 v232, v150, v151
	v_cvt_pk_bf16_f32 v233, v152, v153
	v_cvt_pk_bf16_f32 v234, v146, v147
	v_lshlrev_b64 v[236:237], 1, v[250:251]
	v_mul_f32_e32 v151, v151, v151
	v_fmac_f32_e32 v151, v150, v150
	v_mul_f32_e32 v150, v153, v153
	v_fmac_f32_e32 v150, v152, v152
	v_mul_f32_e32 v147, v147, v147
	v_add_f32_e32 v150, v151, v150
	v_fmac_f32_e32 v147, v146, v146
	v_add_f32_e32 v146, v150, v147
	v_mul_f32_e32 v147, v149, v149
	v_lshl_add_u64 v[238:239], s[6:7], 0, v[236:237]
	v_fmac_f32_e32 v147, v148, v148
	v_pk_add_f32 v[128:129], v[128:129], v[242:243]
	v_pk_add_f32 v[126:127], v[126:127], v[240:241]
	v_cvt_pk_bf16_f32 v235, v148, v149
	s_mov_b64 exec, s[100:101]
	flat_store_dwordx4 v[238:239], v[232:235]
	s_mov_b64 exec, -1
	v_add_f32_e32 v152, v147, v146
	v_pk_add_f32 v[124:125], v[124:125], v[246:247]
	v_pk_add_f32 v[122:123], v[122:123], v[244:245]
	flat_store_dwordx4 v[248:249], v[126:129] offset:512
	flat_store_dwordx4 v[248:249], v[122:125] offset:528
	v_cvt_pk_bf16_f32 v146, v126, v127
	v_cvt_pk_bf16_f32 v147, v128, v129
	v_cvt_pk_bf16_f32 v148, v122, v123
	v_cvt_pk_bf16_f32 v149, v124, v125
	s_nop 0
	v_mul_f32_e32 v127, v127, v127
	v_fmac_f32_e32 v127, v126, v126
	v_mul_f32_e32 v126, v129, v129
	v_fmac_f32_e32 v126, v128, v128
	v_mul_f32_e32 v123, v123, v123
	v_add_f32_e32 v126, v127, v126
	v_fmac_f32_e32 v123, v122, v122
	v_add_f32_e32 v122, v126, v123
	v_mul_f32_e32 v123, v125, v125
	v_fmac_f32_e32 v123, v124, v124
	v_and_b32_e32 v124, 64, v226
	v_add_f32_e32 v122, v123, v122
	v_xor_b32_e32 v123, 16, v226
	v_add_u32_e32 v124, 64, v124
	v_or_b32_e32 v236, 0x100, v236
	v_cmp_lt_i32_e32 vcc, v123, v124
	v_lshl_add_u64 v[150:151], s[6:7], 0, v[236:237]
	s_mov_b64 exec, s[100:101]
	flat_store_dwordx4 v[150:151], v[146:149]
	s_mov_b64 exec, -1
	v_cndmask_b32_e32 v123, v226, v123, vcc
	v_add_f32_e32 v122, v152, v122
	v_lshlrev_b32_e32 v146, 2, v123
	v_mov_b32_e32 v123, v122
	s_nop 1
	v_permlane16_swap_b32 v123, v123
	s_waitcnt lgkmcnt(0)
	v_add_f32_e32 v122, v122, v123
	v_xor_b32_e32 v123, 32, v226
	v_cmp_lt_i32_e32 vcc, v123, v124
	s_nop 1
	v_cndmask_b32_e32 v123, v226, v123, vcc
	v_lshlrev_b32_e32 v147, 2, v123
	v_mov_b32_e32 v123, v122
	s_nop 1
	v_permlane32_swap_b32 v123, v123
	s_and_saveexec_b64 s[50:51], s[38:39]
	s_cbranch_execz .LBB0_1854
	v_lshl_add_u64 v[124:125], v[204:205], 2, s[44:45]
	s_waitcnt lgkmcnt(0)
	v_add_f32_e32 v122, v122, v123
	flat_atomic_add_f32 v[124:125], v122
.LBB0_1854:
	s_or_b64 exec, exec, s[50:51]
	s_waitcnt lgkmcnt(0)
	v_lshlrev_b64 v[122:123], 11, v[214:215]
	v_pk_add_f32 v[112:113], v[112:113], v[176:177]
	v_pk_add_f32 v[110:111], v[110:111], v[174:175]
	v_lshl_add_u64 v[126:127], v[122:123], 0, v[200:201]
	v_pk_add_f32 v[108:109], v[108:109], v[172:173]
	v_pk_add_f32 v[106:107], v[106:107], v[170:171]
	flat_store_dwordx4 v[216:217], v[110:113]
	flat_store_dwordx4 v[216:217], v[106:109] offset:16
	v_cvt_pk_bf16_f32 v122, v110, v111
	v_cvt_pk_bf16_f32 v123, v112, v113
	v_cvt_pk_bf16_f32 v124, v106, v107
	v_pk_add_f32 v[104:105], v[104:105], v[168:169]
	v_mul_f32_e32 v111, v111, v111
	v_fmac_f32_e32 v111, v110, v110
	v_mul_f32_e32 v110, v113, v113
	v_fmac_f32_e32 v110, v112, v112
	v_mul_f32_e32 v107, v107, v107
	v_add_f32_e32 v110, v111, v110
	v_fmac_f32_e32 v107, v106, v106
	v_add_f32_e32 v106, v110, v107
	v_mul_f32_e32 v107, v109, v109
	v_fmac_f32_e32 v107, v108, v108
	v_pk_add_f32 v[102:103], v[102:103], v[166:167]
	v_cvt_pk_bf16_f32 v125, v108, v109
	v_add_f32_e32 v106, v107, v106
	v_mul_f32_e32 v107, v103, v103
	v_mul_f32_e32 v108, v105, v105
	v_pk_add_f32 v[98:99], v[98:99], v[162:163]
	v_fmac_f32_e32 v107, v102, v102
	v_fmac_f32_e32 v108, v104, v104
	v_add_f32_e32 v107, v107, v108
	v_mul_f32_e32 v108, v99, v99
	v_pk_add_f32 v[100:101], v[100:101], v[164:165]
	v_fmac_f32_e32 v108, v98, v98
	v_add_f32_e32 v107, v107, v108
	v_mul_f32_e32 v108, v101, v101
	v_fmac_f32_e32 v108, v100, v100
	v_add_f32_e32 v107, v108, v107
	v_add_f32_e32 v106, v106, v107
	v_mov_b32_e32 v107, v106
	s_nop 1
	v_permlane16_swap_b32 v107, v107
	v_lshlrev_b64 v[126:127], 1, v[126:127]
	v_lshl_add_u64 v[128:129], s[6:7], 0, v[126:127]
	s_mov_b64 exec, s[100:101]
	flat_store_dwordx4 v[128:129], v[122:125]
	s_mov_b64 exec, -1
	flat_store_dwordx4 v[216:217], v[102:105] offset:512
	flat_store_dwordx4 v[216:217], v[98:101] offset:528
	v_or_b32_e32 v126, 0x100, v126
	v_cvt_pk_bf16_f32 v102, v102, v103
	v_cvt_pk_bf16_f32 v103, v104, v105
	v_cvt_pk_bf16_f32 v104, v98, v99
	v_cvt_pk_bf16_f32 v105, v100, v101
	s_waitcnt lgkmcnt(0)
	v_add_f32_e32 v98, v106, v107
	v_mov_b32_e32 v99, v98
	s_nop 1
	v_permlane32_swap_b32 v99, v99
	v_lshl_add_u64 v[100:101], s[6:7], 0, v[126:127]
	s_mov_b64 exec, s[100:101]
	flat_store_dwordx4 v[100:101], v[102:105]
	s_mov_b64 exec, -1
	s_and_saveexec_b64 s[50:51], s[38:39]
	s_cbranch_execz .LBB0_1856
	v_lshl_add_u64 v[100:101], v[214:215], 2, s[44:45]
	s_waitcnt lgkmcnt(0)
	v_add_f32_e32 v98, v98, v99
	flat_atomic_add_f32 v[100:101], v98
.LBB0_1856:
	s_or_b64 exec, exec, s[50:51]
	s_waitcnt lgkmcnt(0)
	v_lshlrev_b64 v[98:99], 11, v[210:211]
	v_pk_add_f32 v[96:97], v[96:97], v[160:161]
	v_pk_add_f32 v[94:95], v[94:95], v[158:159]
	v_lshl_add_u64 v[102:103], v[98:99], 0, v[200:201]
	v_pk_add_f32 v[92:93], v[92:93], v[156:157]
	v_pk_add_f32 v[90:91], v[90:91], v[154:155]
	flat_store_dwordx4 v[212:213], v[94:97]
	flat_store_dwordx4 v[212:213], v[90:93] offset:16
	v_cvt_pk_bf16_f32 v98, v94, v95
	v_cvt_pk_bf16_f32 v99, v96, v97
	v_cvt_pk_bf16_f32 v100, v90, v91
	v_pk_add_f32 v[88:89], v[88:89], v[136:137]
	v_mul_f32_e32 v95, v95, v95
	v_fmac_f32_e32 v95, v94, v94
	v_mul_f32_e32 v94, v97, v97
	v_fmac_f32_e32 v94, v96, v96
	v_mul_f32_e32 v91, v91, v91
	v_add_f32_e32 v94, v95, v94
	v_fmac_f32_e32 v91, v90, v90
	v_add_f32_e32 v90, v94, v91
	v_mul_f32_e32 v91, v93, v93
	v_fmac_f32_e32 v91, v92, v92
	v_pk_add_f32 v[86:87], v[86:87], v[134:135]
	v_cvt_pk_bf16_f32 v101, v92, v93
	v_add_f32_e32 v90, v91, v90
	v_mul_f32_e32 v91, v87, v87
	v_mul_f32_e32 v92, v89, v89
	v_pk_add_f32 v[82:83], v[82:83], v[130:131]
	v_fmac_f32_e32 v91, v86, v86
	v_fmac_f32_e32 v92, v88, v88
	v_add_f32_e32 v91, v91, v92
	v_mul_f32_e32 v92, v83, v83
	v_pk_add_f32 v[84:85], v[84:85], v[132:133]
	v_fmac_f32_e32 v92, v82, v82
	v_add_f32_e32 v91, v91, v92
	v_mul_f32_e32 v92, v85, v85
	v_fmac_f32_e32 v92, v84, v84
	v_add_f32_e32 v91, v92, v91
	v_add_f32_e32 v90, v90, v91
	v_mov_b32_e32 v91, v90
	s_nop 1
	v_permlane16_swap_b32 v91, v91
	v_lshlrev_b64 v[102:103], 1, v[102:103]
	v_lshl_add_u64 v[104:105], s[6:7], 0, v[102:103]
	s_mov_b64 exec, s[100:101]
	flat_store_dwordx4 v[104:105], v[98:101]
	s_mov_b64 exec, -1
	flat_store_dwordx4 v[212:213], v[86:89] offset:512
	flat_store_dwordx4 v[212:213], v[82:85] offset:528
	v_or_b32_e32 v102, 0x100, v102
	v_cvt_pk_bf16_f32 v86, v86, v87
	v_cvt_pk_bf16_f32 v87, v88, v89
	v_cvt_pk_bf16_f32 v88, v82, v83
	v_cvt_pk_bf16_f32 v89, v84, v85
	s_waitcnt lgkmcnt(0)
	v_add_f32_e32 v82, v90, v91
	v_mov_b32_e32 v83, v82
	s_nop 1
	v_permlane32_swap_b32 v83, v83
	v_lshl_add_u64 v[84:85], s[6:7], 0, v[102:103]
	s_mov_b64 exec, s[100:101]
	flat_store_dwordx4 v[84:85], v[86:89]
	s_mov_b64 exec, -1
	s_and_saveexec_b64 s[50:51], s[38:39]
	s_cbranch_execz .LBB0_1858
	v_lshl_add_u64 v[84:85], v[210:211], 2, s[44:45]
	s_waitcnt lgkmcnt(0)
	v_add_f32_e32 v82, v82, v83
	flat_atomic_add_f32 v[84:85], v82
.LBB0_1858:
	s_or_b64 exec, exec, s[50:51]
	s_waitcnt lgkmcnt(0)
	v_lshlrev_b64 v[82:83], 11, v[206:207]
	v_pk_add_f32 v[80:81], v[80:81], v[144:145]
	v_pk_add_f32 v[78:79], v[78:79], v[142:143]
	v_lshl_add_u64 v[86:87], v[82:83], 0, v[200:201]
	v_pk_add_f32 v[76:77], v[76:77], v[140:141]
	v_pk_add_f32 v[74:75], v[74:75], v[138:139]
	flat_store_dwordx4 v[208:209], v[78:81]
	flat_store_dwordx4 v[208:209], v[74:77] offset:16
	v_cvt_pk_bf16_f32 v82, v78, v79
	v_cvt_pk_bf16_f32 v83, v80, v81
	v_cvt_pk_bf16_f32 v84, v74, v75
	v_pk_add_f32 v[72:73], v[72:73], v[120:121]
	v_mul_f32_e32 v79, v79, v79
	v_fmac_f32_e32 v79, v78, v78
	v_mul_f32_e32 v78, v81, v81
	v_fmac_f32_e32 v78, v80, v80
	v_mul_f32_e32 v75, v75, v75
	v_add_f32_e32 v78, v79, v78
	v_fmac_f32_e32 v75, v74, v74
	v_add_f32_e32 v74, v78, v75
	v_mul_f32_e32 v75, v77, v77
	v_fmac_f32_e32 v75, v76, v76
	v_pk_add_f32 v[70:71], v[70:71], v[118:119]
	v_cvt_pk_bf16_f32 v85, v76, v77
	v_add_f32_e32 v74, v75, v74
	v_mul_f32_e32 v75, v71, v71
	v_mul_f32_e32 v76, v73, v73
	v_pk_add_f32 v[66:67], v[66:67], v[114:115]
	v_fmac_f32_e32 v75, v70, v70
	v_fmac_f32_e32 v76, v72, v72
	v_add_f32_e32 v75, v75, v76
	v_mul_f32_e32 v76, v67, v67
	v_pk_add_f32 v[68:69], v[68:69], v[116:117]
	v_fmac_f32_e32 v76, v66, v66
	v_add_f32_e32 v75, v75, v76
	v_mul_f32_e32 v76, v69, v69
	v_fmac_f32_e32 v76, v68, v68
	v_add_f32_e32 v75, v76, v75
	v_add_f32_e32 v74, v74, v75
	v_mov_b32_e32 v75, v74
	s_nop 1
	v_permlane16_swap_b32 v75, v75
	v_lshlrev_b64 v[86:87], 1, v[86:87]
	v_lshl_add_u64 v[88:89], s[6:7], 0, v[86:87]
	s_mov_b64 exec, s[100:101]
	flat_store_dwordx4 v[88:89], v[82:85]
	s_mov_b64 exec, -1
	flat_store_dwordx4 v[208:209], v[70:73] offset:512
	flat_store_dwordx4 v[208:209], v[66:69] offset:528
	v_or_b32_e32 v86, 0x100, v86
	v_cvt_pk_bf16_f32 v70, v70, v71
	v_cvt_pk_bf16_f32 v71, v72, v73
	v_cvt_pk_bf16_f32 v72, v66, v67
	v_cvt_pk_bf16_f32 v73, v68, v69
	s_waitcnt lgkmcnt(0)
	v_add_f32_e32 v66, v74, v75
	v_mov_b32_e32 v67, v66
	s_nop 1
	v_permlane32_swap_b32 v67, v67
	v_lshl_add_u64 v[68:69], s[6:7], 0, v[86:87]
	s_mov_b64 exec, s[100:101]
	flat_store_dwordx4 v[68:69], v[70:73]
	s_mov_b64 exec, -1
	s_and_saveexec_b64 s[50:51], s[38:39]
	s_cbranch_execz .LBB0_1860
	v_lshl_add_u64 v[68:69], v[206:207], 2, s[44:45]
	s_waitcnt lgkmcnt(0)
	v_add_f32_e32 v66, v66, v67
	flat_atomic_add_f32 v[68:69], v66
.LBB0_1860:
	s_or_b64 exec, exec, s[50:51]
	v_add_u32_e32 v134, 0x80, v204
	v_ashrrev_i32_e32 v135, 31, v134
	s_waitcnt lgkmcnt(0)
	v_lshlrev_b64 v[66:67], 13, v[134:135]
	v_lshl_add_u64 v[136:137], v[202:203], 0, v[66:67]
	flat_load_dwordx4 v[138:141], v[136:137]
	flat_load_dwordx4 v[142:145], v[136:137] offset:16
	flat_load_dwordx4 v[118:121], v[136:137] offset:512
	flat_load_dwordx4 v[114:117], v[136:137] offset:528
	v_add_u32_e32 v130, 0x90, v204
	v_ashrrev_i32_e32 v131, 31, v130
	v_add_u32_e32 v126, 0xa0, v204
	v_lshlrev_b64 v[66:67], 13, v[130:131]
	v_ashrrev_i32_e32 v127, 31, v126
	v_add_u32_e32 v122, 0xb0, v204
	v_lshl_add_u64 v[132:133], v[202:203], 0, v[66:67]
	v_lshlrev_b64 v[66:67], 13, v[126:127]
	v_ashrrev_i32_e32 v123, 31, v122
	v_lshl_add_u64 v[128:129], v[202:203], 0, v[66:67]
	v_lshlrev_b64 v[66:67], 13, v[122:123]
	v_lshl_add_u64 v[124:125], v[202:203], 0, v[66:67]
	flat_load_dwordx4 v[110:113], v[132:133]
	flat_load_dwordx4 v[106:109], v[132:133] offset:16
	flat_load_dwordx4 v[102:105], v[132:133] offset:512
	flat_load_dwordx4 v[98:101], v[132:133] offset:528
	flat_load_dwordx4 v[94:97], v[128:129]
	flat_load_dwordx4 v[90:93], v[128:129] offset:16
	flat_load_dwordx4 v[78:81], v[128:129] offset:512
	flat_load_dwordx4 v[74:77], v[128:129] offset:528
	flat_load_dwordx4 v[86:89], v[124:125]
	flat_load_dwordx4 v[82:85], v[124:125] offset:16
	flat_load_dwordx4 v[70:73], v[124:125] offset:512
	flat_load_dwordx4 v[66:69], v[124:125] offset:528
	v_lshlrev_b64 v[148:149], 11, v[134:135]
	v_lshl_add_u64 v[148:149], v[148:149], 0, v[200:201]
	s_waitcnt vmcnt(0) lgkmcnt(0)
	v_pk_add_f32 v[64:65], v[64:65], v[140:141]
	v_pk_add_f32 v[62:63], v[62:63], v[138:139]
	v_pk_add_f32 v[60:61], v[60:61], v[144:145]
	v_pk_add_f32 v[58:59], v[58:59], v[142:143]
	flat_store_dwordx4 v[136:137], v[62:65]
	flat_store_dwordx4 v[136:137], v[58:61] offset:16
	v_cvt_pk_bf16_f32 v138, v62, v63
	v_cvt_pk_bf16_f32 v139, v64, v65
	v_cvt_pk_bf16_f32 v140, v58, v59
	v_lshlrev_b64 v[142:143], 1, v[148:149]
	v_mul_f32_e32 v63, v63, v63
	v_fmac_f32_e32 v63, v62, v62
	v_mul_f32_e32 v62, v65, v65
	v_fmac_f32_e32 v62, v64, v64
	v_mul_f32_e32 v59, v59, v59
	v_add_f32_e32 v62, v63, v62
	v_fmac_f32_e32 v59, v58, v58
	v_add_f32_e32 v58, v62, v59
	v_mul_f32_e32 v59, v61, v61
	v_lshl_add_u64 v[144:145], s[6:7], 0, v[142:143]
	v_fmac_f32_e32 v59, v60, v60
	v_pk_add_f32 v[56:57], v[56:57], v[120:121]
	v_pk_add_f32 v[54:55], v[54:55], v[118:119]
	v_cvt_pk_bf16_f32 v141, v60, v61
	s_mov_b64 exec, s[100:101]
	flat_store_dwordx4 v[144:145], v[138:141]
	s_mov_b64 exec, -1
	v_add_f32_e32 v64, v59, v58
	v_pk_add_f32 v[52:53], v[52:53], v[116:117]
	v_pk_add_f32 v[50:51], v[50:51], v[114:115]
	flat_store_dwordx4 v[136:137], v[54:57] offset:512
	flat_store_dwordx4 v[136:137], v[50:53] offset:528
	v_cvt_pk_bf16_f32 v58, v54, v55
	v_cvt_pk_bf16_f32 v59, v56, v57
	v_cvt_pk_bf16_f32 v60, v50, v51
	v_or_b32_e32 v142, 0x100, v142
	v_mul_f32_e32 v55, v55, v55
	v_fmac_f32_e32 v55, v54, v54
	v_mul_f32_e32 v54, v57, v57
	v_fmac_f32_e32 v54, v56, v56
	v_mul_f32_e32 v51, v51, v51
	v_add_f32_e32 v54, v55, v54
	v_fmac_f32_e32 v51, v50, v50
	v_add_f32_e32 v50, v54, v51
	v_mul_f32_e32 v51, v53, v53
	v_fmac_f32_e32 v51, v52, v52
	v_add_f32_e32 v50, v51, v50
	v_add_f32_e32 v50, v64, v50
	v_mov_b32_e32 v51, v50
	s_nop 1
	v_permlane16_swap_b32 v51, v51
	v_lshl_add_u64 v[62:63], s[6:7], 0, v[142:143]
	v_cvt_pk_bf16_f32 v61, v52, v53
	s_mov_b64 exec, s[100:101]
	flat_store_dwordx4 v[62:63], v[58:61]
	s_mov_b64 exec, -1
	s_waitcnt lgkmcnt(0)
	v_add_f32_e32 v50, v50, v51
	v_mov_b32_e32 v51, v50
	s_nop 1
	v_permlane32_swap_b32 v51, v51
	s_and_saveexec_b64 s[50:51], s[38:39]
	s_cbranch_execz .LBB0_1862
	v_lshl_add_u64 v[52:53], v[134:135], 2, s[44:45]
	s_waitcnt lgkmcnt(0)
	v_add_f32_e32 v50, v50, v51
	flat_atomic_add_f32 v[52:53], v50
.LBB0_1862:
	s_or_b64 exec, exec, s[50:51]
	s_waitcnt lgkmcnt(0)
	v_lshlrev_b64 v[50:51], 11, v[130:131]
	v_pk_add_f32 v[48:49], v[48:49], v[112:113]
	v_pk_add_f32 v[46:47], v[46:47], v[110:111]
	v_lshl_add_u64 v[54:55], v[50:51], 0, v[200:201]
	v_pk_add_f32 v[44:45], v[44:45], v[108:109]
	v_pk_add_f32 v[42:43], v[42:43], v[106:107]
	flat_store_dwordx4 v[132:133], v[46:49]
	flat_store_dwordx4 v[132:133], v[42:45] offset:16
	v_cvt_pk_bf16_f32 v50, v46, v47
	v_cvt_pk_bf16_f32 v51, v48, v49
	v_cvt_pk_bf16_f32 v52, v42, v43
	v_pk_add_f32 v[40:41], v[40:41], v[104:105]
	v_mul_f32_e32 v47, v47, v47
	v_fmac_f32_e32 v47, v46, v46
	v_mul_f32_e32 v46, v49, v49
	v_fmac_f32_e32 v46, v48, v48
	v_mul_f32_e32 v43, v43, v43
	v_add_f32_e32 v46, v47, v46
	v_fmac_f32_e32 v43, v42, v42
	v_add_f32_e32 v42, v46, v43
	v_mul_f32_e32 v43, v45, v45
	v_fmac_f32_e32 v43, v44, v44
	v_pk_add_f32 v[38:39], v[38:39], v[102:103]
	v_cvt_pk_bf16_f32 v53, v44, v45
	v_add_f32_e32 v42, v43, v42
	v_mul_f32_e32 v43, v39, v39
	v_mul_f32_e32 v44, v41, v41
	v_pk_add_f32 v[34:35], v[34:35], v[98:99]
	v_fmac_f32_e32 v43, v38, v38
	v_fmac_f32_e32 v44, v40, v40
	v_add_f32_e32 v43, v43, v44
	v_mul_f32_e32 v44, v35, v35
	v_pk_add_f32 v[36:37], v[36:37], v[100:101]
	v_fmac_f32_e32 v44, v34, v34
	v_add_f32_e32 v43, v43, v44
	v_mul_f32_e32 v44, v37, v37
	v_fmac_f32_e32 v44, v36, v36
	v_add_f32_e32 v43, v44, v43
	v_add_f32_e32 v42, v42, v43
	v_mov_b32_e32 v43, v42
	s_nop 1
	v_permlane16_swap_b32 v43, v43
	v_lshlrev_b64 v[54:55], 1, v[54:55]
	v_lshl_add_u64 v[56:57], s[6:7], 0, v[54:55]
	s_mov_b64 exec, s[100:101]
	flat_store_dwordx4 v[56:57], v[50:53]
	s_mov_b64 exec, -1
	flat_store_dwordx4 v[132:133], v[38:41] offset:512
	flat_store_dwordx4 v[132:133], v[34:37] offset:528
	v_or_b32_e32 v54, 0x100, v54
	v_cvt_pk_bf16_f32 v38, v38, v39
	v_cvt_pk_bf16_f32 v39, v40, v41
	v_cvt_pk_bf16_f32 v40, v34, v35
	v_cvt_pk_bf16_f32 v41, v36, v37
	s_waitcnt lgkmcnt(0)
	v_add_f32_e32 v34, v42, v43
	v_mov_b32_e32 v35, v34
	s_nop 1
	v_permlane32_swap_b32 v35, v35
	v_lshl_add_u64 v[36:37], s[6:7], 0, v[54:55]
	s_mov_b64 exec, s[100:101]
	flat_store_dwordx4 v[36:37], v[38:41]
	s_mov_b64 exec, -1
	s_and_saveexec_b64 s[50:51], s[38:39]
	s_cbranch_execz .LBB0_1864
	v_lshl_add_u64 v[36:37], v[130:131], 2, s[44:45]
	s_waitcnt lgkmcnt(0)
	v_add_f32_e32 v34, v34, v35
	flat_atomic_add_f32 v[36:37], v34
.LBB0_1864:
	s_or_b64 exec, exec, s[50:51]
	s_waitcnt lgkmcnt(0)
	v_lshlrev_b64 v[34:35], 11, v[126:127]
	v_pk_add_f32 v[32:33], v[32:33], v[96:97]
	v_pk_add_f32 v[30:31], v[30:31], v[94:95]
	v_lshl_add_u64 v[38:39], v[34:35], 0, v[200:201]
	v_pk_add_f32 v[28:29], v[28:29], v[92:93]
	v_pk_add_f32 v[26:27], v[26:27], v[90:91]
	flat_store_dwordx4 v[128:129], v[30:33]
	flat_store_dwordx4 v[128:129], v[26:29] offset:16
	v_cvt_pk_bf16_f32 v34, v30, v31
	v_cvt_pk_bf16_f32 v35, v32, v33
	v_cvt_pk_bf16_f32 v36, v26, v27
	v_pk_add_f32 v[24:25], v[24:25], v[80:81]
	v_mul_f32_e32 v31, v31, v31
	v_fmac_f32_e32 v31, v30, v30
	v_mul_f32_e32 v30, v33, v33
	v_fmac_f32_e32 v30, v32, v32
	v_mul_f32_e32 v27, v27, v27
	v_add_f32_e32 v30, v31, v30
	v_fmac_f32_e32 v27, v26, v26
	v_add_f32_e32 v26, v30, v27
	v_mul_f32_e32 v27, v29, v29
	v_fmac_f32_e32 v27, v28, v28
	v_pk_add_f32 v[22:23], v[22:23], v[78:79]
	v_cvt_pk_bf16_f32 v37, v28, v29
	v_add_f32_e32 v26, v27, v26
	v_mul_f32_e32 v27, v23, v23
	v_mul_f32_e32 v28, v25, v25
	v_pk_add_f32 v[18:19], v[18:19], v[74:75]
	v_fmac_f32_e32 v27, v22, v22
	v_fmac_f32_e32 v28, v24, v24
	v_add_f32_e32 v27, v27, v28
	v_mul_f32_e32 v28, v19, v19
	v_pk_add_f32 v[20:21], v[20:21], v[76:77]
	v_fmac_f32_e32 v28, v18, v18
	v_add_f32_e32 v27, v27, v28
	v_mul_f32_e32 v28, v21, v21
	v_fmac_f32_e32 v28, v20, v20
	v_add_f32_e32 v27, v28, v27
	v_add_f32_e32 v26, v26, v27
	v_mov_b32_e32 v27, v26
	s_nop 1
	v_permlane16_swap_b32 v27, v27
	v_lshlrev_b64 v[38:39], 1, v[38:39]
	v_lshl_add_u64 v[40:41], s[6:7], 0, v[38:39]
	s_mov_b64 exec, s[100:101]
	flat_store_dwordx4 v[40:41], v[34:37]
	s_mov_b64 exec, -1
	flat_store_dwordx4 v[128:129], v[22:25] offset:512
	flat_store_dwordx4 v[128:129], v[18:21] offset:528
	v_or_b32_e32 v38, 0x100, v38
	v_cvt_pk_bf16_f32 v22, v22, v23
	v_cvt_pk_bf16_f32 v23, v24, v25
	v_cvt_pk_bf16_f32 v24, v18, v19
	v_cvt_pk_bf16_f32 v25, v20, v21
	s_waitcnt lgkmcnt(0)
	v_add_f32_e32 v18, v26, v27
	v_mov_b32_e32 v19, v18
	s_nop 1
	v_permlane32_swap_b32 v19, v19
	v_lshl_add_u64 v[20:21], s[6:7], 0, v[38:39]
	s_mov_b64 exec, s[100:101]
	flat_store_dwordx4 v[20:21], v[22:25]
	s_mov_b64 exec, -1
	s_and_saveexec_b64 s[50:51], s[38:39]
	s_cbranch_execz .LBB0_1866
	v_lshl_add_u64 v[20:21], v[126:127], 2, s[44:45]
	s_waitcnt lgkmcnt(0)
	v_add_f32_e32 v18, v18, v19
	flat_atomic_add_f32 v[20:21], v18
.LBB0_1866:
	s_or_b64 exec, exec, s[50:51]
	s_waitcnt lgkmcnt(0)
	v_lshlrev_b64 v[18:19], 11, v[122:123]
	v_pk_add_f32 v[16:17], v[16:17], v[88:89]
	v_pk_add_f32 v[14:15], v[14:15], v[86:87]
	v_lshl_add_u64 v[22:23], v[18:19], 0, v[200:201]
	v_pk_add_f32 v[12:13], v[12:13], v[84:85]
	v_pk_add_f32 v[10:11], v[10:11], v[82:83]
	flat_store_dwordx4 v[124:125], v[14:17]
	flat_store_dwordx4 v[124:125], v[10:13] offset:16
	v_cvt_pk_bf16_f32 v18, v14, v15
	v_cvt_pk_bf16_f32 v19, v16, v17
	v_cvt_pk_bf16_f32 v20, v10, v11
	v_pk_add_f32 v[8:9], v[8:9], v[72:73]
	v_mul_f32_e32 v15, v15, v15
	v_fmac_f32_e32 v15, v14, v14
	v_mul_f32_e32 v14, v17, v17
	v_fmac_f32_e32 v14, v16, v16
	v_mul_f32_e32 v11, v11, v11
	v_add_f32_e32 v14, v15, v14
	v_fmac_f32_e32 v11, v10, v10
	v_add_f32_e32 v10, v14, v11
	v_mul_f32_e32 v11, v13, v13
	v_fmac_f32_e32 v11, v12, v12
	v_pk_add_f32 v[6:7], v[6:7], v[70:71]
	v_cvt_pk_bf16_f32 v21, v12, v13
	v_add_f32_e32 v10, v11, v10
	v_mul_f32_e32 v11, v7, v7
	v_mul_f32_e32 v12, v9, v9
	v_pk_add_f32 v[2:3], v[2:3], v[66:67]
	v_fmac_f32_e32 v11, v6, v6
	v_fmac_f32_e32 v12, v8, v8
	v_add_f32_e32 v11, v11, v12
	v_mul_f32_e32 v12, v3, v3
	v_pk_add_f32 v[4:5], v[4:5], v[68:69]
	v_fmac_f32_e32 v12, v2, v2
	v_add_f32_e32 v11, v11, v12
	v_mul_f32_e32 v12, v5, v5
	v_fmac_f32_e32 v12, v4, v4
	v_add_f32_e32 v11, v12, v11
	v_add_f32_e32 v10, v10, v11
	v_mov_b32_e32 v11, v10
	s_nop 1
	v_permlane16_swap_b32 v11, v11
	v_lshlrev_b64 v[22:23], 1, v[22:23]
	v_lshl_add_u64 v[24:25], s[6:7], 0, v[22:23]
	s_mov_b64 exec, s[100:101]
	flat_store_dwordx4 v[24:25], v[18:21]
	s_mov_b64 exec, -1
	flat_store_dwordx4 v[124:125], v[6:9] offset:512
	flat_store_dwordx4 v[124:125], v[2:5] offset:528
	v_or_b32_e32 v22, 0x100, v22
	v_cvt_pk_bf16_f32 v6, v6, v7
	v_cvt_pk_bf16_f32 v7, v8, v9
	v_cvt_pk_bf16_f32 v8, v2, v3
	v_cvt_pk_bf16_f32 v9, v4, v5
	s_waitcnt lgkmcnt(0)
	v_add_f32_e32 v2, v10, v11
	v_mov_b32_e32 v3, v2
	s_nop 1
	v_permlane32_swap_b32 v3, v3
	v_lshl_add_u64 v[4:5], s[6:7], 0, v[22:23]
	s_mov_b64 exec, s[100:101]
	flat_store_dwordx4 v[4:5], v[6:9]
	s_mov_b64 exec, -1
	s_and_saveexec_b64 s[50:51], s[38:39]
	s_cbranch_execz .LBB0_1868
	v_lshl_add_u64 v[4:5], v[122:123], 2, s[44:45]
	s_waitcnt lgkmcnt(0)
	v_add_f32_e32 v2, v2, v3
	flat_atomic_add_f32 v[4:5], v2
